# first half-step QK: 12 (was 20) softmax VALU units in front of its first MFMA
# baseline (speedup 1.0000x reference)
; __device__ __forceinline__ void finishSM(f32x16& p0, f32x16& p1, float alpha, float& l_reg, bf16x8& pa0, bf16x8& pa1, bf16x8& pa2, bf16x8& pa3) {
;     for (int r = 0; r < 16; ++r) p1[r] = __builtin_amdgcn_exp2f(p1[r]);
;     float ps = 0; for (int r = 0; r < 16; ++r) ps += p0[r]; for (int r = 0; r < 16; ++r) ps += p1[r];
;     { auto rr = __builtin_amdgcn_permlane32_swap(__float_as_uint(ps), __float_as_uint(ps), false, false);
;       ps = __uint_as_float(rr[0]) + __uint_as_float(rr[1]); }
;     l_reg = l_reg * alpha + ps;
;     ...
;     PK4(p0, 0, pa0); PK4(p0, 8, pa1); PK4(p1, 0, pa2); PK4(p1, 8, pa3);
; template <int KB>
; __device__ __forceinline__ void qkt(f32x16& p0, f32x16& p1, const char* K_lds, int r32, int hi, const bf16x8* qr) {
;     p0 = f32x16{}; p1 = f32x16{};
;     const char* kb[4];
; #pragma unroll
;     for (int dd = 0; dd < 4; ++dd) kb[dd] = K_lds + KB * SHM_K + KSWZ(r32, (dd * 16 + hi * 8) * 2);
; #pragma unroll
;     for (int d0 = 0; d0 < 8; ++d0) { const char* a = kb[d0 & 3] + (d0 >> 2) * 128;
;         bf16x8 b0 = *reinterpret_cast<const bf16x8*>(a);
;         bf16x8 b1 = *reinterpret_cast<const bf16x8*>(a + 32 * 256);
;         p0 = __builtin_amdgcn_mfma_f32_32x32x16_bf16(b0, qr[d0], p0, 0, 0, 0);
;         p1 = __builtin_amdgcn_mfma_f32_32x32x16_bf16(b1, qr[d0], p1, 0, 0, 0); }
; }
.LBB0_89:
	ds_read_b128 v[66:69], v169 offset:49152
	ds_read_b128 v[70:73], v169 offset:57344
	ds_read_b128 v[100:103], v193 offset:49152
	ds_read_b128 v[136:139], v193 offset:57344
	ds_read_b128 v[234:237], v194 offset:49152
	ds_read_b128 v[238:241], v194 offset:57344
	v_add_f32_e32 v148, 0, v231
	v_add_f32_e32 v148, v233, v148
	v_add_f32_e32 v148, v229, v148
	v_add_f32_e32 v148, v232, v148
	v_add_f32_e32 v148, v228, v148
	v_add_f32_e32 v148, v230, v148
	v_add_f32_e32 v148, v226, v148
	v_add_f32_e32 v148, v227, v148
	v_add_f32_e32 v148, v223, v148
	v_add_f32_e32 v148, v225, v148
	v_add_f32_e32 v148, v209, v148
	v_add_f32_e32 v148, v224, v148
	s_waitcnt lgkmcnt(5)
	v_mfma_f32_32x32x16_bf16 v[82:97], v[66:69], v[132:135], 0
	v_add_f32_e32 v148, v206, v148
	v_add_f32_e32 v148, v208, v148
	v_add_f32_e32 v148, v205, v148
	v_add_f32_e32 v148, v207, v148
	v_exp_f32_e32 v140, v152
	s_waitcnt lgkmcnt(4)
	v_mfma_f32_32x32x16_bf16 v[66:81], v[70:73], v[132:135], 0
	v_exp_f32_e32 v141, v153
	v_exp_f32_e32 v142, v180
	v_exp_f32_e32 v143, v181
	v_exp_f32_e32 v144, v160
	s_waitcnt lgkmcnt(3)
	v_mfma_f32_32x32x16_bf16 v[82:97], v[100:103], v[128:131], v[82:97]
	v_exp_f32_e32 v145, v161
	v_exp_f32_e32 v146, v154
	v_exp_f32_e32 v147, v155
	v_exp_f32_e32 v178, v178
	s_waitcnt lgkmcnt(2)
	v_mfma_f32_32x32x16_bf16 v[66:81], v[136:139], v[128:131], v[66:81]
	v_exp_f32_e32 v179, v179
	v_exp_f32_e32 v162, v162
	v_exp_f32_e32 v163, v163
	v_add_f32_e32 v148, v178, v148
	ds_read_b128 v[100:103], v195 offset:49152
	ds_read_b128 v[136:139], v195 offset:57344
	s_waitcnt lgkmcnt(3)
	v_mfma_f32_32x32x16_bf16 v[82:97], v[234:237], v[124:127], v[82:97]
	v_add_f32_e32 v148, v179, v148
	v_add_f32_e32 v148, v162, v148
	v_exp_f32_e32 v158, v158
	v_exp_f32_e32 v159, v159
	s_waitcnt lgkmcnt(2)
	v_mfma_f32_32x32x16_bf16 v[66:81], v[238:241], v[124:127], v[66:81]
	v_exp_f32_e32 v156, v156
	v_exp_f32_e32 v157, v157
	v_add_f32_e32 v148, v163, v148
	v_add_f32_e32 v148, v158, v148
	ds_read_b128 v[234:237], v169 offset:49280
	ds_read_b128 v[238:241], v169 offset:57472
	s_waitcnt lgkmcnt(3)
	v_mfma_f32_32x32x16_bf16 v[82:97], v[100:103], v[120:123], v[82:97]
	v_add_f32_e32 v148, v159, v148
	v_add_f32_e32 v148, v156, v148
	v_add_f32_e32 v148, v157, v148
	v_add_f32_e32 v148, v140, v148
	s_waitcnt lgkmcnt(2)
	v_mfma_f32_32x32x16_bf16 v[66:81], v[136:139], v[120:123], v[66:81]
	v_add_f32_e32 v148, v141, v148
	v_add_f32_e32 v148, v142, v148
	v_add_f32_e32 v148, v143, v148
	v_add_f32_e32 v148, v144, v148
	ds_read_b128 v[100:103], v193 offset:49280
	ds_read_b128 v[136:139], v193 offset:57472
	s_waitcnt lgkmcnt(3)
	v_mfma_f32_32x32x16_bf16 v[82:97], v[234:237], v[116:119], v[82:97]
	v_add_f32_e32 v148, v145, v148
	v_add_f32_e32 v148, v146, v148
	v_add_f32_e32 v199, v147, v148
	v_mov_b32_e32 v200, v199
	s_nop 1
	v_permlane32_swap_b32_e32 v199, v200
	s_waitcnt lgkmcnt(2)
	v_mfma_f32_32x32x16_bf16 v[66:81], v[238:241], v[116:119], v[66:81]
	v_cvt_pk_bf16_f32 v148, v231, v233
	v_cvt_pk_bf16_f32 v149, v229, v232
	v_cvt_pk_bf16_f32 v150, v228, v230
	v_cvt_pk_bf16_f32 v151, v226, v227
	ds_read_b128 v[234:237], v194 offset:49280
	ds_read_b128 v[238:241], v194 offset:57472
	s_waitcnt lgkmcnt(3)
	v_mfma_f32_32x32x16_bf16 v[82:97], v[100:103], v[112:115], v[82:97]
	v_cvt_pk_bf16_f32 v152, v223, v225
	v_cvt_pk_bf16_f32 v153, v209, v224
	v_cvt_pk_bf16_f32 v154, v206, v208
	v_cvt_pk_bf16_f32 v155, v205, v207
	s_waitcnt lgkmcnt(2)
	v_mfma_f32_32x32x16_bf16 v[66:81], v[136:139], v[112:115], v[66:81]
	v_cvt_pk_bf16_f32 v158, v158, v159
	v_cvt_pk_bf16_f32 v159, v156, v157
	v_cvt_pk_bf16_f32 v156, v178, v179
	v_cvt_pk_bf16_f32 v157, v162, v163
	ds_read_b128 v[100:103], v195 offset:49280
	ds_read_b128 v[136:139], v195 offset:57472
	ds_read_b64_tr_b16 v[172:173], v185 offset:0
	ds_read_b64_tr_b16 v[174:175], v185 offset:0x800
	ds_read_b64_tr_b16 v[202:203], v185 offset:0x1000
	ds_read_b64_tr_b16 v[204:205], v185 offset:0x1800
	ds_read_b64_tr_b16 v[206:207], v185 offset:0x2000
	ds_read_b64_tr_b16 v[208:209], v185 offset:0x2800
	ds_read_b64_tr_b16 v[224:225], v185 offset:0x3000
	ds_read_b64_tr_b16 v[226:227], v185 offset:0x3800
	s_waitcnt lgkmcnt(11)
	v_mfma_f32_32x32x16_bf16 v[82:97], v[234:237], v[108:111], v[82:97]
	v_cvt_pk_bf16_f32 v160, v140, v141
	v_cvt_pk_bf16_f32 v161, v142, v143
	v_cvt_pk_bf16_f32 v162, v144, v145
	v_cvt_pk_bf16_f32 v163, v146, v147
	s_waitcnt lgkmcnt(10)
	v_mfma_f32_32x32x16_bf16 v[66:81], v[238:241], v[108:111], v[66:81]
	s_nop 0
	v_permlane32_swap_b32_e32 v148, v150
	v_permlane32_swap_b32_e32 v149, v151
	v_permlane32_swap_b32_e32 v152, v154
	v_permlane32_swap_b32_e32 v153, v155
	s_waitcnt lgkmcnt(9)
	v_mfma_f32_32x32x16_bf16 v[82:97], v[100:103], v[104:107], v[82:97]
	v_permlane32_swap_b32_e32 v156, v158
	v_permlane32_swap_b32_e32 v157, v159
	v_permlane32_swap_b32_e32 v160, v162
	v_permlane32_swap_b32_e32 v161, v163
	s_waitcnt lgkmcnt(8)
	v_mfma_f32_32x32x16_bf16 v[66:81], v[136:139], v[104:107], v[66:81]
	v_add_u32_e32 v169, s100, v169
	v_add_u32_e32 v193, s100, v193
	v_add_u32_e32 v194, s100, v194
	v_add_u32_e32 v195, s100, v195
	s_sub_i32 s100, 0, s100
	s_sub_i32 m0, 0, s100
	s_max_i32 m0, m0, 0
	s_add_i32 m0, m0, s32
	s_add_i32 m0, m0, 0x4000
	s_nop 0
	global_load_lds_dwordx4 v[244:245], off
	s_add_i32 m0, m0, 0x2000
	s_nop 0
	global_load_lds_dwordx4 v[246:247], off
	v_lshl_add_u64 v[244:245], v[244:245], 0, v[250:251]
	v_lshl_add_u64 v[246:247], v[246:247], 0, v[250:251]
	s_sub_i32 m0, 0, s100
	s_max_i32 m0, m0, 0
	s_add_i32 m0, m0, s32
	s_add_i32 m0, m0, s32
	s_sub_i32 m0, m0, 0x10000
	s_nop 0
	global_load_lds_dwordx4 v[248:249], off
	s_add_i32 m0, m0, 896
	s_nop 0
	global_load_lds_dwordx4 v[248:249], off offset:128
	v_lshl_add_u64 v[248:249], v[248:249], 0, v[250:251]
	s_nop 0
	s_waitcnt lgkmcnt(6)
; __device__ __forceinline__ void mask_tile(f32x16& p0, f32x16& p1, int dq, unsigned W) {
;     const float NEG = -__builtin_inff();
; #pragma unroll
;     for (int r = 0; r < 16; ++r) {
;         const int c = (r & 3) + 8 * (r >> 2);
;         if ((unsigned)(dq - c) >= W) p0[r] = NEG;
;         if ((unsigned)(dq - c - 32) >= W) p1[r] = NEG;
;     }
; }
; template <int VB>
; __device__ __forceinline__ void pv_tile(f32x16* o, int vb0, bf16x8 pa0, bf16x8 pa1, bf16x8 pa2, bf16x8 pa3) {
;     ...
;     PV_D0(0); PV_D0(1); PV_D0(2); PV_D0(3);
	v_mfma_f32_32x32x16_bf16 v[50:65], v[148:151], v[172:175], v[50:65]
	ds_read_b64_tr_b16 v[172:173], v185 offset:0x200
	ds_read_b64_tr_b16 v[174:175], v185 offset:0xa00
	s_waitcnt lgkmcnt(6)
	v_mfma_f32_32x32x16_bf16 v[50:65], v[152:155], v[202:205], v[50:65]
	ds_read_b64_tr_b16 v[202:203], v185 offset:0x1200
	ds_read_b64_tr_b16 v[204:205], v185 offset:0x1a00
	s_waitcnt lgkmcnt(6)
	v_mfma_f32_32x32x16_bf16 v[50:65], v[156:159], v[206:209], v[50:65]
	ds_read_b64_tr_b16 v[206:207], v185 offset:0x2200
	ds_read_b64_tr_b16 v[208:209], v185 offset:0x2a00
	s_waitcnt lgkmcnt(6)
	v_mfma_f32_32x32x16_bf16 v[50:65], v[160:163], v[224:227], v[50:65]
	ds_read_b64_tr_b16 v[224:225], v185 offset:0x3200
	ds_read_b64_tr_b16 v[226:227], v185 offset:0x3a00
	s_waitcnt lgkmcnt(6)
	v_mfma_f32_32x32x16_bf16 v[34:49], v[148:151], v[172:175], v[34:49]
	ds_read_b64_tr_b16 v[172:173], v185 offset:0x400
	ds_read_b64_tr_b16 v[174:175], v185 offset:0xc00
	s_waitcnt lgkmcnt(6)
	v_mfma_f32_32x32x16_bf16 v[34:49], v[152:155], v[202:205], v[34:49]
	ds_read_b64_tr_b16 v[202:203], v185 offset:0x1400
	ds_read_b64_tr_b16 v[204:205], v185 offset:0x1c00
	s_waitcnt lgkmcnt(6)
	v_mfma_f32_32x32x16_bf16 v[34:49], v[156:159], v[206:209], v[34:49]
	ds_read_b64_tr_b16 v[206:207], v185 offset:0x2400
	ds_read_b64_tr_b16 v[208:209], v185 offset:0x2c00
	s_waitcnt lgkmcnt(6)
	v_mfma_f32_32x32x16_bf16 v[34:49], v[160:163], v[224:227], v[34:49]
	ds_read_b64_tr_b16 v[224:225], v185 offset:0x3400
	ds_read_b64_tr_b16 v[226:227], v185 offset:0x3c00
	s_waitcnt lgkmcnt(6)
	v_mfma_f32_32x32x16_bf16 v[18:33], v[148:151], v[172:175], v[18:33]
	ds_read_b64_tr_b16 v[172:173], v185 offset:0x600
	ds_read_b64_tr_b16 v[174:175], v185 offset:0xe00
	s_waitcnt lgkmcnt(6)
	v_mfma_f32_32x32x16_bf16 v[18:33], v[152:155], v[202:205], v[18:33]
	ds_read_b64_tr_b16 v[202:203], v185 offset:0x1600
	ds_read_b64_tr_b16 v[204:205], v185 offset:0x1e00
	s_waitcnt lgkmcnt(6)
	v_mfma_f32_32x32x16_bf16 v[18:33], v[156:159], v[206:209], v[18:33]
	ds_read_b64_tr_b16 v[206:207], v185 offset:0x2600
	ds_read_b64_tr_b16 v[208:209], v185 offset:0x2e00
	s_waitcnt lgkmcnt(6)
	v_mfma_f32_32x32x16_bf16 v[18:33], v[160:163], v[224:227], v[18:33]
	ds_read_b64_tr_b16 v[224:225], v185 offset:0x3600
	ds_read_b64_tr_b16 v[226:227], v185 offset:0x3e00
	s_waitcnt lgkmcnt(6)
	v_mfma_f32_32x32x16_bf16 v[2:17], v[148:151], v[172:175], v[2:17]
	s_cmp_le_i32 s7, s6
	s_waitcnt lgkmcnt(4)
	v_mfma_f32_32x32x16_bf16 v[2:17], v[152:155], v[202:205], v[2:17]
	s_waitcnt lgkmcnt(2)
	v_mfma_f32_32x32x16_bf16 v[2:17], v[156:159], v[206:209], v[2:17]
	s_waitcnt lgkmcnt(0)
	v_mfma_f32_32x32x16_bf16 v[2:17], v[160:163], v[224:227], v[2:17]
	s_cbranch_scc1 .LBB0_91
	v_add_u32_e32 v148, 0x4000007b, v197
	v_cmp_gt_u32_e32 vcc, 2.0, v148
	v_add_u32_e32 v148, 0x5b, v197
	s_nop 0
	v_cndmask_b32_e32 v82, v220, v82, vcc
	v_cmp_lt_u32_e32 vcc, s33, v148
	v_add_u32_e32 v148, 0x7a, v197
	s_nop 0
	v_cndmask_b32_e32 v66, v220, v66, vcc
	v_cmp_lt_u32_e32 vcc, s33, v148
	v_add_u32_e32 v148, 0x5a, v197
	s_nop 0
	v_cndmask_b32_e32 v83, v220, v83, vcc
	v_cmp_lt_u32_e32 vcc, s33, v148
	v_add_u32_e32 v148, 0x79, v197
	s_nop 0
	v_cndmask_b32_e32 v67, v220, v67, vcc
	v_cmp_lt_u32_e32 vcc, s33, v148
	v_add_u32_e32 v148, 0x59, v197
	s_nop 0
	v_cndmask_b32_e32 v84, v220, v84, vcc
	v_cmp_lt_u32_e32 vcc, s33, v148
	v_add_u32_e32 v148, 0x78, v197
	s_nop 0
	v_cndmask_b32_e32 v68, v220, v68, vcc
	v_cmp_lt_u32_e32 vcc, s33, v148
	v_add_u32_e32 v148, 0x58, v197
	s_nop 0
	v_cndmask_b32_e32 v85, v220, v85, vcc
	v_cmp_lt_u32_e32 vcc, s33, v148
	v_add_u32_e32 v148, 0x73, v197
	s_nop 0
	v_cndmask_b32_e32 v69, v220, v69, vcc
	v_cmp_lt_u32_e32 vcc, s33, v148
	v_add_u32_e32 v148, 0x53, v197
	s_nop 0
	v_cndmask_b32_e32 v86, v220, v86, vcc
	v_cmp_lt_u32_e32 vcc, s33, v148
	v_add_u32_e32 v148, 0x72, v197
	s_nop 0
	v_cndmask_b32_e32 v70, v220, v70, vcc
	v_cmp_lt_u32_e32 vcc, s33, v148
	v_add_u32_e32 v148, 0x52, v197
	s_nop 0
	v_cndmask_b32_e32 v87, v220, v87, vcc
	v_cmp_lt_u32_e32 vcc, s33, v148
	v_add_u32_e32 v148, 0x71, v197
	s_nop 0
	v_cndmask_b32_e32 v71, v220, v71, vcc
	v_cmp_lt_u32_e32 vcc, s33, v148
	v_add_u32_e32 v148, 0x51, v197
	s_nop 0
	v_cndmask_b32_e32 v88, v220, v88, vcc
	v_cmp_lt_u32_e32 vcc, s33, v148
	v_add_u32_e32 v148, 0x70, v197
	s_nop 0
	v_cndmask_b32_e32 v72, v220, v72, vcc
	v_cmp_lt_u32_e32 vcc, s33, v148
	v_add_u32_e32 v148, 0x50, v197
	s_nop 0
	v_cndmask_b32_e32 v89, v220, v89, vcc
	v_cmp_lt_u32_e32 vcc, s33, v148
	v_add_u32_e32 v148, 0x6b, v197
	s_nop 0
	v_cndmask_b32_e32 v73, v220, v73, vcc
	v_cmp_lt_u32_e32 vcc, s33, v148
	v_add_u32_e32 v148, 0x4b, v197
	s_nop 0
	v_cndmask_b32_e32 v90, v220, v90, vcc
	v_cmp_lt_u32_e32 vcc, s33, v148
	v_add_u32_e32 v148, 0x6a, v197
	s_nop 0
	v_cndmask_b32_e32 v74, v220, v74, vcc
	v_cmp_lt_u32_e32 vcc, s33, v148
	v_add_u32_e32 v148, 0x4a, v197
	s_nop 0
	v_cndmask_b32_e32 v91, v220, v91, vcc
	v_cmp_lt_u32_e32 vcc, s33, v148
	v_add_u32_e32 v148, 0x69, v197
	s_nop 0
	v_cndmask_b32_e32 v75, v220, v75, vcc
	v_cmp_lt_u32_e32 vcc, s33, v148
	v_add_u32_e32 v148, 0x49, v197
	s_nop 0
	v_cndmask_b32_e32 v92, v220, v92, vcc
	v_cmp_lt_u32_e32 vcc, s33, v148
	v_add_u32_e32 v148, 0x68, v197
	s_nop 0
	v_cndmask_b32_e32 v76, v220, v76, vcc
	v_cmp_lt_u32_e32 vcc, s33, v148
	v_add_u32_e32 v148, 0x48, v197
	s_nop 0
	v_cndmask_b32_e32 v93, v220, v93, vcc
	v_cmp_lt_u32_e32 vcc, s33, v148
	v_add_u32_e32 v148, 0x63, v197
	s_nop 0
	v_cndmask_b32_e32 v77, v220, v77, vcc
	v_cmp_lt_u32_e32 vcc, s33, v148
	v_add_u32_e32 v148, 0x43, v197
	s_nop 0
	v_cndmask_b32_e32 v94, v220, v94, vcc
	v_cmp_lt_u32_e32 vcc, s33, v148
	v_add_u32_e32 v148, 0x62, v197
	s_nop 0
	v_cndmask_b32_e32 v78, v220, v78, vcc
	v_cmp_lt_u32_e32 vcc, s33, v148
	v_add_u32_e32 v148, 0x42, v197
	s_nop 0
	v_cndmask_b32_e32 v95, v220, v95, vcc
	v_cmp_lt_u32_e32 vcc, s33, v148
	v_add_u32_e32 v148, 0x61, v197
	s_nop 0
	v_cndmask_b32_e32 v79, v220, v79, vcc
	v_cmp_lt_u32_e32 vcc, s33, v148
	v_add_u32_e32 v148, 0x41, v197
	s_nop 0
	v_cndmask_b32_e32 v96, v220, v96, vcc
	v_cmp_lt_u32_e32 vcc, s33, v148
	v_add_u32_e32 v148, 0x60, v197
	s_nop 0
	v_cndmask_b32_e32 v80, v220, v80, vcc
	v_cmp_lt_u32_e32 vcc, s33, v148
	v_add_u32_e32 v148, 64, v197
	s_nop 0
	v_cndmask_b32_e32 v97, v220, v97, vcc
	v_cmp_lt_u32_e32 vcc, s33, v148
	s_nop 1
	v_cndmask_b32_e32 v81, v220, v81, vcc
